# code placement: the P1/P4 K-loop heads at byte offset 44 mod 64 (the phase the baseline's P1 loop has)
# speedup vs baseline: 1.0071x; 1.0071x over previous
; template <class Epi, class Sched, bool ALIGN_EPI = false, bool SP2 = false>
; __device__ __forceinline__ void gemm_phase(PG8_LAS unsigned char* lds, const Gemm g, const Sched& S, const Epi& E) {
;     ...
;         const bool has_next = S.next(ui + 1, nxt);
;         const char* nA = has_next ? (const char*)g.A + (size_t)nxt.pm * tstep : cA; const char* nB = has_next ? (const char*)g.Bt + (size_t)nxt.pn * tstep : cB;
;         for (int t = 0; t < nt; t += 2) {
;             const bool last = (t == nt - 2);
;             const char* a1 = cA + (size_t)(t + 1) * kstep;
;             const char* a2 = last ? nA : cA + (size_t)(t + 2) * kstep; const char* b2 = last ? nB : cB + (size_t)(t + 2) * kstep;
;     ...
; #pragma unroll
;         for (int a = 0; a < 2; ++a)
; #pragma unroll
;             for (int b = 0; b < 2; ++b)
; #pragma unroll
;                 for (int m = 0; m < 4; ++m)
; #pragma unroll
;                     for (int n = 0; n < 2; ++n) acc[a][b][m][n] = (f32x4){0.f, 0.f, 0.f, 0.f};
.LBB0_161:
	s_ashr_i32 s41, s40, 31
	s_lshl_b64 s[34:35], s[40:41], 19
	s_add_u32 s42, s68, s34
	s_addc_u32 s43, s69, s35
	s_and_b64 s[34:35], s[0:1], exec
	s_cselect_b32 s5, s43, s49
	s_cselect_b32 s34, s42, s48
	s_ashr_i32 s27, s26, 31
	s_lshl_b64 s[44:45], s[26:27], 19
	s_add_u32 s44, s70, s44
	s_addc_u32 s45, s71, s45
	s_and_b64 s[64:65], s[0:1], exec
	s_cselect_b32 s27, s45, s51
	s_cselect_b32 s35, s44, s50
	s_add_u32 s48, s48, 0x40080
	s_addc_u32 s49, s49, 0
	s_add_u32 s41, s50, 0x100
	v_mov_b32_e32 v2, 0
	s_addc_u32 s92, s51, 0
	s_mov_b32 s93, -2
	v_mov_b32_e32 v3, v2
	s_cmp_lg_u32 s76, 1
	s_cbranch_scc1 .Lp1_peel
	v_mov_b32_e32 v4, v2
	v_mov_b32_e32 v5, v2
	v_mov_b32_e32 v6, v2
	v_mov_b32_e32 v7, v2
	v_mov_b32_e32 v8, v2
	v_mov_b32_e32 v9, v2
	v_mov_b32_e32 v18, v2
	v_mov_b32_e32 v19, v2
	v_mov_b32_e32 v20, v2
	v_mov_b32_e32 v21, v2
	v_mov_b32_e32 v22, v2
	v_mov_b32_e32 v23, v2
	v_mov_b32_e32 v24, v2
	v_mov_b32_e32 v25, v2
	v_mov_b32_e32 v34, v2
	v_mov_b32_e32 v35, v2
	v_mov_b32_e32 v36, v2
	v_mov_b32_e32 v37, v2
	v_mov_b32_e32 v38, v2
	v_mov_b32_e32 v39, v2
	v_mov_b32_e32 v40, v2
	v_mov_b32_e32 v41, v2
	v_mov_b32_e32 v50, v2
	v_mov_b32_e32 v51, v2
	v_mov_b32_e32 v52, v2
	v_mov_b32_e32 v53, v2
	v_mov_b32_e32 v54, v2
	v_mov_b32_e32 v55, v2
	v_mov_b32_e32 v56, v2
	v_mov_b32_e32 v57, v2
	v_mov_b32_e32 v10, v2
	v_mov_b32_e32 v11, v2
	v_mov_b32_e32 v12, v2
	v_mov_b32_e32 v13, v2
	v_mov_b32_e32 v14, v2
	v_mov_b32_e32 v15, v2
	v_mov_b32_e32 v16, v2
	v_mov_b32_e32 v17, v2
	v_mov_b32_e32 v26, v2
	v_mov_b32_e32 v27, v2
	v_mov_b32_e32 v28, v2
	v_mov_b32_e32 v29, v2
	v_mov_b32_e32 v30, v2
	v_mov_b32_e32 v31, v2
	v_mov_b32_e32 v32, v2
	v_mov_b32_e32 v33, v2
	v_mov_b32_e32 v42, v2
	v_mov_b32_e32 v43, v2
	v_mov_b32_e32 v44, v2
	v_mov_b32_e32 v45, v2
	v_mov_b32_e32 v46, v2
	v_mov_b32_e32 v47, v2
	v_mov_b32_e32 v48, v2
	v_mov_b32_e32 v49, v2
	v_mov_b32_e32 v58, v2
	v_mov_b32_e32 v59, v2
	v_mov_b32_e32 v60, v2
	v_mov_b32_e32 v61, v2
	v_mov_b32_e32 v62, v2
	v_mov_b32_e32 v63, v2
	v_mov_b32_e32 v64, v2
	v_mov_b32_e32 v65, v2
	v_mov_b32_e32 v66, v2
	v_mov_b32_e32 v67, v2
	v_mov_b32_e32 v68, v2
	v_mov_b32_e32 v69, v2
	v_mov_b32_e32 v70, v2
	v_mov_b32_e32 v71, v2
	v_mov_b32_e32 v72, v2
	v_mov_b32_e32 v73, v2
	v_mov_b32_e32 v82, v2
	v_mov_b32_e32 v83, v2
	v_mov_b32_e32 v84, v2
	v_mov_b32_e32 v85, v2
	v_mov_b32_e32 v86, v2
	v_mov_b32_e32 v87, v2
	v_mov_b32_e32 v88, v2
	v_mov_b32_e32 v89, v2
	v_mov_b32_e32 v98, v2
	v_mov_b32_e32 v99, v2
	v_mov_b32_e32 v100, v2
	v_mov_b32_e32 v101, v2
	v_mov_b32_e32 v102, v2
	v_mov_b32_e32 v103, v2
	v_mov_b32_e32 v104, v2
	v_mov_b32_e32 v105, v2
	v_mov_b32_e32 v114, v2
	v_mov_b32_e32 v115, v2
	v_mov_b32_e32 v116, v2
	v_mov_b32_e32 v117, v2
	v_mov_b32_e32 v118, v2
	v_mov_b32_e32 v119, v2
	v_mov_b32_e32 v120, v2
	v_mov_b32_e32 v121, v2
	v_mov_b32_e32 v74, v2
	v_mov_b32_e32 v75, v2
	v_mov_b32_e32 v76, v2
	v_mov_b32_e32 v77, v2
	v_mov_b32_e32 v78, v2
	v_mov_b32_e32 v79, v2
	v_mov_b32_e32 v80, v2
	v_mov_b32_e32 v81, v2
	v_mov_b32_e32 v90, v2
	v_mov_b32_e32 v91, v2
	v_mov_b32_e32 v92, v2
	v_mov_b32_e32 v93, v2
	v_mov_b32_e32 v94, v2
	v_mov_b32_e32 v95, v2
	v_mov_b32_e32 v96, v2
	v_mov_b32_e32 v97, v2
	v_mov_b32_e32 v106, v2
	v_mov_b32_e32 v107, v2
	v_mov_b32_e32 v108, v2
	v_mov_b32_e32 v109, v2
	v_mov_b32_e32 v110, v2
	v_mov_b32_e32 v111, v2
	v_mov_b32_e32 v112, v2
	v_mov_b32_e32 v113, v2
	v_mov_b32_e32 v122, v2
	v_mov_b32_e32 v123, v2
	v_mov_b32_e32 v124, v2
	v_mov_b32_e32 v125, v2
	v_mov_b32_e32 v126, v2
	v_mov_b32_e32 v127, v2
	v_mov_b32_e32 v128, v2
	v_mov_b32_e32 v129, v2
	.p2align	6
	s_nop 0
	s_nop 0
	s_nop 0
	s_nop 0
	s_nop 0
	s_nop 0
	s_nop 0
	s_nop 0
	s_nop 0
	s_nop 0
	s_nop 0

; template <class Epi, class Sched, bool ALIGN_EPI = false, bool SP2 = false>
; __device__ __forceinline__ void gemm_phase(PG8_LAS unsigned char* lds, const Gemm g, const Sched& S, const Epi& E) {
;     ...
;         const bool has_next = S.next(ui + 1, nxt);
;         const char* nA = has_next ? (const char*)g.A + (size_t)nxt.pm * tstep : cA; const char* nB = has_next ? (const char*)g.Bt + (size_t)nxt.pn * tstep : cB;
;         for (int t = 0; t < nt; t += 2) {
;             const bool last = (t == nt - 2);
;             const char* a1 = cA + (size_t)(t + 1) * kstep;
;             const char* a2 = last ? nA : cA + (size_t)(t + 2) * kstep; const char* b2 = last ? nB : cB + (size_t)(t + 2) * kstep;
;     ...
; #pragma unroll
;         for (int a = 0; a < 2; ++a)
; #pragma unroll
;             for (int b = 0; b < 2; ++b)
; #pragma unroll
;                 for (int m = 0; m < 4; ++m)
; #pragma unroll
;                     for (int n = 0; n < 2; ++n) acc[a][b][m][n] = (f32x4){0.f, 0.f, 0.f, 0.f};
.LBB0_456:
	s_ashr_i32 s25, s24, 31
	s_lshl_b64 s[26:27], s[24:25], 19
	s_add_u32 s26, s33, s26
	s_addc_u32 s27, s42, s27
	s_and_b64 s[28:29], s[0:1], exec
	s_cselect_b32 s25, s27, s35
	s_cselect_b32 s61, s26, s34
	s_ashr_i32 s21, s20, 31
	s_lshl_b64 s[28:29], s[20:21], 19
	s_add_u32 s28, s43, s28
	s_addc_u32 s29, s44, s29
	s_and_b64 s[38:39], s[0:1], exec
	s_cselect_b32 s21, s29, s41
	s_cselect_b32 s62, s28, s40
	s_add_u32 s34, s34, 0x40080
	s_addc_u32 s35, s35, 0
	s_add_u32 s63, s40, 0x100
	v_mov_b32_e32 v0, 0
	s_addc_u32 s64, s41, 0
	s_mov_b32 s65, -2
	v_mov_b32_e32 v1, v0
	s_cmp_lg_u32 s51, 1
	s_cbranch_scc1 .Lp4_peel
	v_mov_b32_e32 v2, v0
	v_mov_b32_e32 v3, v0
	v_mov_b32_e32 v4, v0
	v_mov_b32_e32 v5, v0
	v_mov_b32_e32 v6, v0
	v_mov_b32_e32 v7, v0
	v_mov_b32_e32 v8, v0
	v_mov_b32_e32 v9, v0
	v_mov_b32_e32 v10, v0
	v_mov_b32_e32 v11, v0
	v_mov_b32_e32 v16, v0
	v_mov_b32_e32 v17, v0
	v_mov_b32_e32 v18, v0
	v_mov_b32_e32 v19, v0
	v_mov_b32_e32 v28, v0
	v_mov_b32_e32 v29, v0
	v_mov_b32_e32 v30, v0
	v_mov_b32_e32 v31, v0
	v_mov_b32_e32 v32, v0
	v_mov_b32_e32 v33, v0
	v_mov_b32_e32 v34, v0
	v_mov_b32_e32 v35, v0
	v_mov_b32_e32 v40, v0
	v_mov_b32_e32 v41, v0
	v_mov_b32_e32 v42, v0
	v_mov_b32_e32 v43, v0
	v_mov_b32_e32 v44, v0
	v_mov_b32_e32 v45, v0
	v_mov_b32_e32 v46, v0
	v_mov_b32_e32 v47, v0
	v_mov_b32_e32 v12, v0
	v_mov_b32_e32 v13, v0
	v_mov_b32_e32 v14, v0
	v_mov_b32_e32 v15, v0
	v_mov_b32_e32 v20, v0
	v_mov_b32_e32 v21, v0
	v_mov_b32_e32 v22, v0
	v_mov_b32_e32 v23, v0
	v_mov_b32_e32 v24, v0
	v_mov_b32_e32 v25, v0
	v_mov_b32_e32 v26, v0
	v_mov_b32_e32 v27, v0
	v_mov_b32_e32 v36, v0
	v_mov_b32_e32 v37, v0
	v_mov_b32_e32 v38, v0
	v_mov_b32_e32 v39, v0
	v_mov_b32_e32 v48, v0
	v_mov_b32_e32 v49, v0
	v_mov_b32_e32 v50, v0
	v_mov_b32_e32 v51, v0
	v_mov_b32_e32 v52, v0
	v_mov_b32_e32 v53, v0
	v_mov_b32_e32 v54, v0
	v_mov_b32_e32 v55, v0
	v_mov_b32_e32 v56, v0
	v_mov_b32_e32 v57, v0
	v_mov_b32_e32 v58, v0
	v_mov_b32_e32 v59, v0
	v_mov_b32_e32 v60, v0
	v_mov_b32_e32 v61, v0
	v_mov_b32_e32 v62, v0
	v_mov_b32_e32 v63, v0
	v_mov_b32_e32 v64, v0
	v_mov_b32_e32 v65, v0
	v_mov_b32_e32 v66, v0
	v_mov_b32_e32 v67, v0
	v_mov_b32_e32 v68, v0
	v_mov_b32_e32 v69, v0
	v_mov_b32_e32 v70, v0
	v_mov_b32_e32 v71, v0
	v_mov_b32_e32 v72, v0
	v_mov_b32_e32 v73, v0
	v_mov_b32_e32 v74, v0
	v_mov_b32_e32 v75, v0
	v_mov_b32_e32 v80, v0
	v_mov_b32_e32 v81, v0
	v_mov_b32_e32 v82, v0
	v_mov_b32_e32 v83, v0
	v_mov_b32_e32 v92, v0
	v_mov_b32_e32 v93, v0
	v_mov_b32_e32 v94, v0
	v_mov_b32_e32 v95, v0
	v_mov_b32_e32 v100, v0
	v_mov_b32_e32 v101, v0
	v_mov_b32_e32 v102, v0
	v_mov_b32_e32 v103, v0
	v_mov_b32_e32 v104, v0
	v_mov_b32_e32 v105, v0
	v_mov_b32_e32 v106, v0
	v_mov_b32_e32 v107, v0
	v_mov_b32_e32 v108, v0
	v_mov_b32_e32 v109, v0
	v_mov_b32_e32 v110, v0
	v_mov_b32_e32 v111, v0
	v_mov_b32_e32 v76, v0
	v_mov_b32_e32 v77, v0
	v_mov_b32_e32 v78, v0
	v_mov_b32_e32 v79, v0
	v_mov_b32_e32 v84, v0
	v_mov_b32_e32 v85, v0
	v_mov_b32_e32 v86, v0
	v_mov_b32_e32 v87, v0
	v_mov_b32_e32 v88, v0
	v_mov_b32_e32 v89, v0
	v_mov_b32_e32 v90, v0
	v_mov_b32_e32 v91, v0
	v_mov_b32_e32 v96, v0
	v_mov_b32_e32 v97, v0
	v_mov_b32_e32 v98, v0
	v_mov_b32_e32 v99, v0
	v_mov_b32_e32 v112, v0
	v_mov_b32_e32 v113, v0
	v_mov_b32_e32 v114, v0
	v_mov_b32_e32 v115, v0
	v_mov_b32_e32 v116, v0
	v_mov_b32_e32 v117, v0
	v_mov_b32_e32 v118, v0
	v_mov_b32_e32 v119, v0
	v_mov_b32_e32 v120, v0
	v_mov_b32_e32 v121, v0
	v_mov_b32_e32 v122, v0
	v_mov_b32_e32 v123, v0
	v_mov_b32_e32 v124, v0
	v_mov_b32_e32 v125, v0
	v_mov_b32_e32 v126, v0
	v_mov_b32_e32 v127, v0
	.p2align	6
	s_nop 0
	s_nop 0
	s_nop 0
	s_nop 0
	s_nop 0
	s_nop 0
	s_nop 0
	s_nop 0
	s_nop 0
	s_nop 0
	s_nop 0
